# attention epilogue: O tile transposed through LDS, 8 global_store_dwordx4 per lane instead of 64 global_store_short
# baseline (speedup 1.0000x reference)
; __device__ __forceinline__ unsigned cvt_pk_bf16(float lo, float hi) { unsigned r; asm volatile("v_cvt_pk_bf16_f32 %0, %1, %2" : "=v"(r) : "v"(lo), "v"(hi)); return r; }
; __device__ __forceinline__ int crow(int r, int hi) { return (r & 3) + 8 * (r >> 2) + 4 * hi; }
; template <bool MLA> ...
;     ...
;   if (hi == 0) li_l[r32] = l_reg; asm volatile("s_waitcnt lgkmcnt(0)" ::: "memory");
;   float rli[16];
; #pragma unroll
;   for (int r = 0; r < 16; ++r) rli[r] = __builtin_amdgcn_rcpf(li_l[crow(r, hi)]);
;   bf16_t* Ow = Ob + (long)(wid * QBLK) * LDO;
; #pragma unroll
;   for (int r = 0; r < 16; ++r) { int orow = crow(r, hi);
; #pragma unroll
;     for (int d0 = 0; d0 < 4; ++d0) Ow[(long)orow * LDO + d0 * 32 + r32] = (bf16_t)(cvt_pk_bf16(o[d0][r] * rli[r], 0.f) & 0xffffu); }
.LBB0_97:
	s_or_b64 exec, exec, s[2:3]
	s_waitcnt lgkmcnt(0)
	v_add_u32_e32 v0, s10, v166
	ds_read_b128 v[66:69], v0
	ds_read_b128 v[70:73], v0 offset:32
	ds_read_b128 v[74:77], v0 offset:64
	ds_read_b128 v[78:81], v0 offset:96
	s_mul_hi_i32 s3, s11, 0x1800
	s_mulk_i32 s11, 0x1800
	s_add_u32 s2, s4, s11
	s_addc_u32 s3, s5, s3
	v_and_b32_e32 v83, 0x1c0, v184
	v_lshlrev_b32_e32 v83, 7, v83
	v_and_b32_e32 v82, 32, v184
	v_lshl_or_b32 v83, v82, 5, v83
	v_and_b32_e32 v82, 31, v184
	v_lshl_or_b32 v83, v82, 1, v83
	s_waitcnt lgkmcnt(0)
	s_barrier
	v_rcp_f32_e32 v66, v66
	v_rcp_f32_e32 v67, v67
	v_rcp_f32_e32 v68, v68
	v_rcp_f32_e32 v69, v69
	v_rcp_f32_e32 v70, v70
	v_rcp_f32_e32 v71, v71
	v_rcp_f32_e32 v72, v72
	v_rcp_f32_e32 v73, v73
	v_rcp_f32_e32 v74, v74
	v_rcp_f32_e32 v75, v75
	v_rcp_f32_e32 v76, v76
	v_rcp_f32_e32 v77, v77
	v_rcp_f32_e32 v78, v78
	v_rcp_f32_e32 v79, v79
	v_rcp_f32_e32 v80, v80
	v_rcp_f32_e32 v81, v81
	s_nop 0
	v_mul_f32_e32 v82, v2, v66
	v_cvt_pk_bf16_f32 v82, v82, v1
	ds_write_b16 v83, v82 offset:0
	v_mul_f32_e32 v0, v50, v66
	v_cvt_pk_bf16_f32 v0, v0, v1
	ds_write_b16 v83, v0 offset:64
	v_mul_f32_e32 v82, v34, v66
	v_cvt_pk_bf16_f32 v82, v82, v1
	ds_write_b16 v83, v82 offset:128
	v_mul_f32_e32 v0, v18, v66
	v_cvt_pk_bf16_f32 v0, v0, v1
	ds_write_b16 v83, v0 offset:192
	v_mul_f32_e32 v82, v3, v67
	v_cvt_pk_bf16_f32 v82, v82, v1
	ds_write_b16 v83, v82 offset:256
	v_mul_f32_e32 v0, v51, v67
	v_cvt_pk_bf16_f32 v0, v0, v1
	ds_write_b16 v83, v0 offset:320
	v_mul_f32_e32 v82, v35, v67
	v_cvt_pk_bf16_f32 v82, v82, v1
	ds_write_b16 v83, v82 offset:384
	v_mul_f32_e32 v0, v19, v67
	v_cvt_pk_bf16_f32 v0, v0, v1
	ds_write_b16 v83, v0 offset:448
	v_mul_f32_e32 v82, v4, v68
	v_cvt_pk_bf16_f32 v82, v82, v1
	ds_write_b16 v83, v82 offset:512
	v_mul_f32_e32 v0, v52, v68
	v_cvt_pk_bf16_f32 v0, v0, v1
	ds_write_b16 v83, v0 offset:576
	v_mul_f32_e32 v82, v36, v68
	v_cvt_pk_bf16_f32 v82, v82, v1
	ds_write_b16 v83, v82 offset:640
	v_mul_f32_e32 v0, v20, v68
	v_cvt_pk_bf16_f32 v0, v0, v1
	ds_write_b16 v83, v0 offset:704
	v_mul_f32_e32 v82, v5, v69
	v_cvt_pk_bf16_f32 v82, v82, v1
	ds_write_b16 v83, v82 offset:768
	v_mul_f32_e32 v0, v53, v69
	v_cvt_pk_bf16_f32 v0, v0, v1
	ds_write_b16 v83, v0 offset:832
	v_mul_f32_e32 v82, v37, v69
	v_cvt_pk_bf16_f32 v82, v82, v1
	ds_write_b16 v83, v82 offset:896
	v_mul_f32_e32 v0, v21, v69
	v_cvt_pk_bf16_f32 v0, v0, v1
	ds_write_b16 v83, v0 offset:960
	v_mul_f32_e32 v82, v6, v70
	v_cvt_pk_bf16_f32 v82, v82, v1
	ds_write_b16 v83, v82 offset:2048
	v_mul_f32_e32 v0, v54, v70
	v_cvt_pk_bf16_f32 v0, v0, v1
	ds_write_b16 v83, v0 offset:2112
	v_mul_f32_e32 v82, v38, v70
	v_cvt_pk_bf16_f32 v82, v82, v1
	ds_write_b16 v83, v82 offset:2176
	v_mul_f32_e32 v0, v22, v70
	v_cvt_pk_bf16_f32 v0, v0, v1
	ds_write_b16 v83, v0 offset:2240
	v_mul_f32_e32 v82, v7, v71
	v_cvt_pk_bf16_f32 v82, v82, v1
	ds_write_b16 v83, v82 offset:2304
	v_mul_f32_e32 v0, v55, v71
	v_cvt_pk_bf16_f32 v0, v0, v1
	ds_write_b16 v83, v0 offset:2368
	v_mul_f32_e32 v82, v39, v71
	v_cvt_pk_bf16_f32 v82, v82, v1
	ds_write_b16 v83, v82 offset:2432
	v_mul_f32_e32 v0, v23, v71
	v_cvt_pk_bf16_f32 v0, v0, v1
	ds_write_b16 v83, v0 offset:2496
	v_mul_f32_e32 v82, v8, v72
	v_cvt_pk_bf16_f32 v82, v82, v1
	ds_write_b16 v83, v82 offset:2560
	v_mul_f32_e32 v0, v56, v72
	v_cvt_pk_bf16_f32 v0, v0, v1
	ds_write_b16 v83, v0 offset:2624
	v_mul_f32_e32 v82, v40, v72
	v_cvt_pk_bf16_f32 v82, v82, v1
	ds_write_b16 v83, v82 offset:2688
	v_mul_f32_e32 v0, v24, v72
	v_cvt_pk_bf16_f32 v0, v0, v1
	ds_write_b16 v83, v0 offset:2752
	v_mul_f32_e32 v82, v9, v73
	v_cvt_pk_bf16_f32 v82, v82, v1
	ds_write_b16 v83, v82 offset:2816
	v_mul_f32_e32 v0, v57, v73
	v_cvt_pk_bf16_f32 v0, v0, v1
	ds_write_b16 v83, v0 offset:2880
	v_mul_f32_e32 v82, v41, v73
	v_cvt_pk_bf16_f32 v82, v82, v1
	ds_write_b16 v83, v82 offset:2944
	v_mul_f32_e32 v0, v25, v73
	v_cvt_pk_bf16_f32 v0, v0, v1
	ds_write_b16 v83, v0 offset:3008
	v_mul_f32_e32 v82, v10, v74
	v_cvt_pk_bf16_f32 v82, v82, v1
	ds_write_b16 v83, v82 offset:4096
	v_mul_f32_e32 v0, v58, v74
	v_cvt_pk_bf16_f32 v0, v0, v1
	ds_write_b16 v83, v0 offset:4160
	v_mul_f32_e32 v82, v42, v74
	v_cvt_pk_bf16_f32 v82, v82, v1
	ds_write_b16 v83, v82 offset:4224
	v_mul_f32_e32 v0, v26, v74
	v_cvt_pk_bf16_f32 v0, v0, v1
	ds_write_b16 v83, v0 offset:4288
	v_mul_f32_e32 v82, v11, v75
	v_cvt_pk_bf16_f32 v82, v82, v1
	ds_write_b16 v83, v82 offset:4352
	v_mul_f32_e32 v0, v59, v75
	v_cvt_pk_bf16_f32 v0, v0, v1
	ds_write_b16 v83, v0 offset:4416
	v_mul_f32_e32 v82, v43, v75
	v_cvt_pk_bf16_f32 v82, v82, v1
	ds_write_b16 v83, v82 offset:4480
	v_mul_f32_e32 v0, v27, v75
	v_cvt_pk_bf16_f32 v0, v0, v1
	ds_write_b16 v83, v0 offset:4544
	v_mul_f32_e32 v82, v12, v76
	v_cvt_pk_bf16_f32 v82, v82, v1
	ds_write_b16 v83, v82 offset:4608
	v_mul_f32_e32 v0, v60, v76
	v_cvt_pk_bf16_f32 v0, v0, v1
	ds_write_b16 v83, v0 offset:4672
	v_mul_f32_e32 v82, v44, v76
	v_cvt_pk_bf16_f32 v82, v82, v1
	ds_write_b16 v83, v82 offset:4736
	v_mul_f32_e32 v0, v28, v76
	v_cvt_pk_bf16_f32 v0, v0, v1
	ds_write_b16 v83, v0 offset:4800
	v_mul_f32_e32 v82, v13, v77
	v_cvt_pk_bf16_f32 v82, v82, v1
	ds_write_b16 v83, v82 offset:4864
	v_mul_f32_e32 v0, v61, v77
	v_cvt_pk_bf16_f32 v0, v0, v1
	ds_write_b16 v83, v0 offset:4928
	v_mul_f32_e32 v82, v45, v77
	v_cvt_pk_bf16_f32 v82, v82, v1
	ds_write_b16 v83, v82 offset:4992
	v_mul_f32_e32 v0, v29, v77
	v_cvt_pk_bf16_f32 v0, v0, v1
	ds_write_b16 v83, v0 offset:5056
	v_mul_f32_e32 v82, v14, v78
	v_cvt_pk_bf16_f32 v82, v82, v1
	ds_write_b16 v83, v82 offset:6144
	v_mul_f32_e32 v0, v62, v78
	v_cvt_pk_bf16_f32 v0, v0, v1
	ds_write_b16 v83, v0 offset:6208
	v_mul_f32_e32 v82, v46, v78
	v_cvt_pk_bf16_f32 v82, v82, v1
	ds_write_b16 v83, v82 offset:6272
	v_mul_f32_e32 v0, v30, v78
	v_cvt_pk_bf16_f32 v0, v0, v1
	ds_write_b16 v83, v0 offset:6336
	v_mul_f32_e32 v82, v15, v79
	v_cvt_pk_bf16_f32 v82, v82, v1
	ds_write_b16 v83, v82 offset:6400
	v_mul_f32_e32 v0, v63, v79
	v_cvt_pk_bf16_f32 v0, v0, v1
	ds_write_b16 v83, v0 offset:6464
	v_mul_f32_e32 v82, v47, v79
	v_cvt_pk_bf16_f32 v82, v82, v1
	ds_write_b16 v83, v82 offset:6528
	v_mul_f32_e32 v0, v31, v79
	v_cvt_pk_bf16_f32 v0, v0, v1
	ds_write_b16 v83, v0 offset:6592
	v_mul_f32_e32 v82, v16, v80
	v_cvt_pk_bf16_f32 v82, v82, v1
	ds_write_b16 v83, v82 offset:6656
	v_mul_f32_e32 v0, v64, v80
	v_cvt_pk_bf16_f32 v0, v0, v1
	ds_write_b16 v83, v0 offset:6720
	v_mul_f32_e32 v82, v48, v80
	v_cvt_pk_bf16_f32 v82, v82, v1
	ds_write_b16 v83, v82 offset:6784
	v_mul_f32_e32 v0, v32, v80
	v_cvt_pk_bf16_f32 v0, v0, v1
	ds_write_b16 v83, v0 offset:6848
	v_mul_f32_e32 v82, v17, v81
	v_cvt_pk_bf16_f32 v82, v82, v1
	ds_write_b16 v83, v82 offset:6912
	v_mul_f32_e32 v0, v65, v81
	v_cvt_pk_bf16_f32 v0, v0, v1
	ds_write_b16 v83, v0 offset:6976
	v_mul_f32_e32 v82, v49, v81
	v_cvt_pk_bf16_f32 v82, v82, v1
	ds_write_b16 v83, v82 offset:7040
	v_mul_f32_e32 v0, v33, v81
	v_cvt_pk_bf16_f32 v0, v0, v1
	ds_write_b16 v83, v0 offset:7104
	s_waitcnt lgkmcnt(0)
; __device__ __forceinline__ unsigned cvt_pk_bf16(float lo, float hi) { unsigned r; asm volatile("v_cvt_pk_bf16_f32 %0, %1, %2" : "=v"(r) : "v"(lo), "v"(hi)); return r; }
; __device__ __forceinline__ int crow(int r, int hi) { return (r & 3) + 8 * (r >> 2) + 4 * hi; }
; template <bool MLA> ...
;     ...
;   bf16_t* Ow = Ob + (long)(wid * QBLK) * LDO;
; #pragma unroll
;   for (int r = 0; r < 16; ++r) { int orow = crow(r, hi);
; #pragma unroll
;     for (int d0 = 0; d0 < 4; ++d0) Ow[(long)orow * LDO + d0 * 32 + r32] = (bf16_t)(cvt_pk_bf16(o[d0][r] * rli[r], 0.f) & 0xffffu); }
;   __syncthreads();
	v_and_b32_e32 v2, 0x1c0, v184
	v_lshlrev_b32_e32 v2, 7, v2
	v_and_b32_e32 v3, 63, v184
	v_lshl_or_b32 v2, v3, 4, v2
	ds_read_b128 v[4:7], v2 offset:0
	ds_read_b128 v[8:11], v2 offset:1024
	ds_read_b128 v[12:15], v2 offset:2048
	ds_read_b128 v[16:19], v2 offset:3072
	ds_read_b128 v[20:23], v2 offset:4096
	ds_read_b128 v[24:27], v2 offset:5120
	ds_read_b128 v[28:31], v2 offset:6144
	ds_read_b128 v[32:35], v2 offset:7168
	v_bfe_u32 v36, v184, 4, 2
	v_mul_u32_u24_e32 v36, 0x1800, v36
	v_and_b32_e32 v37, 15, v184
	v_lshl_or_b32 v36, v37, 4, v36
	v_mov_b32_e32 v37, 0
	v_lshl_add_u64 v[38:39], s[2:3], 0, v[36:37]
	s_mov_b64 vcc, 0x6000
	v_lshl_add_u64 v[40:41], v[38:39], 0, vcc
	v_lshl_add_u64 v[42:43], v[40:41], 0, vcc
	v_lshl_add_u64 v[44:45], v[42:43], 0, vcc
	v_lshl_add_u64 v[46:47], v[44:45], 0, vcc
	v_lshl_add_u64 v[48:49], v[46:47], 0, vcc
	v_lshl_add_u64 v[50:51], v[48:49], 0, vcc
	v_lshl_add_u64 v[52:53], v[50:51], 0, vcc
	s_waitcnt lgkmcnt(7)
	global_store_dwordx4 v[38:39], v[4:7], off
	s_waitcnt lgkmcnt(6)
	global_store_dwordx4 v[40:41], v[8:11], off
	s_waitcnt lgkmcnt(5)
	global_store_dwordx4 v[42:43], v[12:15], off
	s_waitcnt lgkmcnt(4)
	global_store_dwordx4 v[44:45], v[16:19], off
	s_waitcnt lgkmcnt(3)
	global_store_dwordx4 v[46:47], v[20:23], off
	s_waitcnt lgkmcnt(2)
	global_store_dwordx4 v[48:49], v[24:27], off
	s_waitcnt lgkmcnt(1)
	global_store_dwordx4 v[50:51], v[28:31], off
	s_waitcnt lgkmcnt(0)
	global_store_dwordx4 v[52:53], v[32:35], off
	s_waitcnt vmcnt(63) expcnt(7) lgkmcnt(15)
	s_barrier

; __device__ __forceinline__ void finishSM(f32x16& p0, f32x16& p1, float alpha, float& l_reg, bf16x8& pa0, bf16x8& pa1, bf16x8& pa2, bf16x8& pa3) {
; #pragma unroll
;   for (int r = 0; r < 16; ++r) p1[r] = __builtin_amdgcn_exp2f(p1[r]);
;   float ps = 0;
; #pragma unroll
;   for (int r = 0; r < 16; ++r) ps += p0[r];
; #pragma unroll
;   for (int r = 0; r < 16; ++r) ps += p1[r];
;   { auto rr = __builtin_amdgcn_permlane32_swap(__float_as_uint(ps), __float_as_uint(ps), false, false);
;     ps = __uint_as_float(rr[0]) + __uint_as_float(rr[1]); }
;   l_reg = l_reg * alpha + ps;
;     ...
;   PK4(p0, 0, pa0); PK4(p0, 8, pa1); PK4(p1, 0, pa2); PK4(p1, 8, pa3);
;     ...
; }
; template <bool MLA>
; __device__ __forceinline__ void qkt(f32x16& p0, f32x16& p1, const char* Ks, const char* KRs, const bf16x8* qr, const char* qrl, const f32x16& negm, int r32, int hi) {
; #pragma unroll
;   for (int d0 = 0; d0 < 8; ++d0) { int cb = (d0 * 16 + hi * 8) * 2;
;     bf16x8 b0 = *reinterpret_cast<const bf16x8*>(Ks + KSWZ(r32, cb));
;     bf16x8 b1 = *reinterpret_cast<const bf16x8*>(Ks + KSWZ(32 + r32, cb));
;     if (d0 == 0) { p0 = __builtin_amdgcn_mfma_f32_32x32x16_bf16(b0, qr[0], negm, 0, 0, 0); p1 = __builtin_amdgcn_mfma_f32_32x32x16_bf16(b1, qr[0], negm, 0, 0, 0); }
;     else { p0 = __builtin_amdgcn_mfma_f32_32x32x16_bf16(b0, qr[d0], p0, 0, 0, 0); p1 = __builtin_amdgcn_mfma_f32_32x32x16_bf16(b1, qr[d0], p1, 0, 0, 0); } }
;   if constexpr (MLA) {
; #pragma unroll
;     for (int d0 = 0; d0 < 4; ++d0) { int ch = d0 * 2 + hi;
;       bf16x8 b0 = *reinterpret_cast<const bf16x8*>(KRs + KRSWZ(r32, ch));
;       bf16x8 b1 = *reinterpret_cast<const bf16x8*>(KRs + KRSWZ(32 + r32, ch));
;       const bf16x8 qq = *reinterpret_cast<const bf16x8*>(qrl + d0 * 1024);
;       p0 = __builtin_amdgcn_mfma_f32_32x32x16_bf16(b0, qq, p0, 0, 0, 0);
;       p1 = __builtin_amdgcn_mfma_f32_32x32x16_bf16(b1, qq, p1, 0, 0, 0); }
;   }
; }
; __device__ __forceinline__ int v_st(int k, int c) { const int kk = (k & ~0xC) | ((k & 4) << 1) | ((k & 8) >> 1); return ((kk >> 3) * 4 + (c >> 5)) * 512 + ((kk & 7) * 32 + (c & 31)) * 2; }
; __device__ __forceinline__ int v_rd_base(int lane) { return ((lane & 3) << 3) | (((lane >> 2) & 3) << 6) | (((lane >> 4) & 1) << 5) | (((lane >> 5) & 1) << 8); }
; template <int OFF> __device__ __forceinline__ s16x4 tr_read(int vb) {
.LBB0_121:
	v_exp_f32_e32 v68, v114
	v_exp_f32_e32 v69, v115
	v_exp_f32_e32 v70, v116
	v_exp_f32_e32 v71, v117
	v_exp_f32_e32 v72, v118
	v_add_f32_e32 v66, 0, v68
	v_exp_f32_e32 v73, v119
	v_add_f32_e32 v66, v69, v66
	v_exp_f32_e32 v74, v120
	v_add_f32_e32 v66, v70, v66
	v_exp_f32_e32 v75, v121
	v_add_f32_e32 v66, v71, v66
	v_exp_f32_e32 v76, v122
	v_add_f32_e32 v66, v72, v66
	v_exp_f32_e32 v77, v123
	v_add_f32_e32 v66, v73, v66
	v_exp_f32_e32 v78, v124
	v_add_f32_e32 v66, v74, v66
	v_exp_f32_e32 v79, v125
	v_add_f32_e32 v66, v75, v66
	v_exp_f32_e32 v80, v126
	v_add_f32_e32 v66, v76, v66
	v_exp_f32_e32 v81, v127
	v_add_f32_e32 v66, v77, v66
	v_exp_f32_e32 v84, v128
	v_add_f32_e32 v66, v78, v66
	v_exp_f32_e32 v85, v129
	v_add_f32_e32 v66, v79, v66
	v_exp_f32_e32 v86, v98
	v_add_f32_e32 v66, v80, v66
	v_exp_f32_e32 v87, v99
	v_add_f32_e32 v66, v81, v66
	v_exp_f32_e32 v88, v100
	v_add_f32_e32 v66, v84, v66
	v_exp_f32_e32 v89, v101
	v_add_f32_e32 v66, v85, v66
	v_exp_f32_e32 v90, v102
	v_add_f32_e32 v66, v86, v66
	v_exp_f32_e32 v91, v103
	v_add_f32_e32 v66, v87, v66
	v_exp_f32_e32 v92, v104
	v_add_f32_e32 v66, v88, v66
	v_exp_f32_e32 v93, v105
	v_add_f32_e32 v66, v89, v66
	v_exp_f32_e32 v94, v106
	v_add_f32_e32 v66, v90, v66
	v_exp_f32_e32 v95, v107
	v_add_f32_e32 v66, v91, v66
	v_exp_f32_e32 v96, v108
	v_add_f32_e32 v66, v92, v66
	v_exp_f32_e32 v97, v109
	v_add_f32_e32 v66, v93, v66
	v_exp_f32_e32 v98, v110
	v_add_f32_e32 v66, v94, v66
	v_exp_f32_e32 v99, v111
	v_add_f32_e32 v66, v95, v66
	v_exp_f32_e32 v100, v112
	v_add_f32_e32 v66, v96, v66
	v_exp_f32_e32 v101, v113
	v_add_f32_e32 v66, v97, v66
	v_add_f32_e32 v66, v98, v66
	v_add_f32_e32 v66, v99, v66
	v_add_f32_e32 v66, v100, v66
	v_add_f32_e32 v66, v101, v66
	v_mov_b32_e32 v67, v66
	s_nop 1
	v_permlane32_swap_b32_e32 v66, v67
	v_cvt_pk_bf16_f32 v68, v68, v69
	v_cvt_pk_bf16_f32 v69, v70, v71
	v_cvt_pk_bf16_f32 v70, v72, v73
	v_cvt_pk_bf16_f32 v71, v74, v75
	v_cvt_pk_bf16_f32 v72, v76, v77
	v_cvt_pk_bf16_f32 v73, v78, v79
	v_cvt_pk_bf16_f32 v74, v80, v81
	v_cvt_pk_bf16_f32 v75, v84, v85
	v_cvt_pk_bf16_f32 v76, v86, v87
	v_cvt_pk_bf16_f32 v77, v88, v89
	v_cvt_pk_bf16_f32 v78, v90, v91
	v_cvt_pk_bf16_f32 v79, v92, v93
	v_cvt_pk_bf16_f32 v84, v94, v95
	v_cvt_pk_bf16_f32 v85, v96, v97
	v_cvt_pk_bf16_f32 v86, v98, v99
	v_cvt_pk_bf16_f32 v87, v100, v101
	s_nop 0
	v_permlane32_swap_b32_e32 v68, v70
	v_permlane32_swap_b32_e32 v69, v71
	v_permlane32_swap_b32_e32 v72, v74
	v_permlane32_swap_b32_e32 v73, v75
	v_permlane32_swap_b32_e32 v76, v78
	v_permlane32_swap_b32_e32 v77, v79
	v_permlane32_swap_b32_e32 v84, v86
	v_permlane32_swap_b32_e32 v85, v87
	s_cmp_lg_u32 0, -1
	s_cselect_b32 s2, 0, 0
	s_addk_i32 s2, 0x4000
	v_add_u32_e32 v80, s2, v196
	ds_read_b64_tr_b16 v[88:89], v80 offset:0
	ds_read_b64_tr_b16 v[90:91], v80 offset:0x800
	ds_read_b64_tr_b16 v[92:93], v80 offset:0x1000
	ds_read_b64_tr_b16 v[94:95], v80 offset:0x1800
	ds_read_b64_tr_b16 v[96:97], v80 offset:0x2000
	ds_read_b64_tr_b16 v[98:99], v80 offset:0x2800
	ds_read_b64_tr_b16 v[100:101], v80 offset:0x3000
	ds_read_b64_tr_b16 v[102:103], v80 offset:0x3800
	s_waitcnt lgkmcnt(0)
	s_nop 0
	v_mfma_f32_32x32x16_bf16 v[50:65], v[68:71], v[88:91], v[50:65]
	ds_read_b64_tr_b16 v[88:89], v80 offset:0x200
	ds_read_b64_tr_b16 v[90:91], v80 offset:0xa00
	v_mfma_f32_32x32x16_bf16 v[50:65], v[72:75], v[92:95], v[50:65]
	ds_read_b64_tr_b16 v[92:93], v80 offset:0x1200
	ds_read_b64_tr_b16 v[94:95], v80 offset:0x1a00
	v_mfma_f32_32x32x16_bf16 v[50:65], v[76:79], v[96:99], v[50:65]
	ds_read_b64_tr_b16 v[96:97], v80 offset:0x2200
	ds_read_b64_tr_b16 v[98:99], v80 offset:0x2a00
	v_mfma_f32_32x32x16_bf16 v[50:65], v[84:87], v[100:103], v[50:65]
	ds_read_b64_tr_b16 v[100:101], v80 offset:0x3200
	ds_read_b64_tr_b16 v[102:103], v80 offset:0x3a00
	s_waitcnt lgkmcnt(0)
	v_mfma_f32_32x32x16_bf16 v[34:49], v[68:71], v[88:91], v[34:49]
	ds_read_b64_tr_b16 v[88:89], v80 offset:0x400
	ds_read_b64_tr_b16 v[90:91], v80 offset:0xc00
	v_mfma_f32_32x32x16_bf16 v[34:49], v[72:75], v[92:95], v[34:49]
	ds_read_b64_tr_b16 v[92:93], v80 offset:0x1400
	ds_read_b64_tr_b16 v[94:95], v80 offset:0x1c00
	v_mfma_f32_32x32x16_bf16 v[34:49], v[76:79], v[96:99], v[34:49]
	ds_read_b64_tr_b16 v[96:97], v80 offset:0x2400
	ds_read_b64_tr_b16 v[98:99], v80 offset:0x2c00
	v_mfma_f32_32x32x16_bf16 v[34:49], v[84:87], v[100:103], v[34:49]
	ds_read_b64_tr_b16 v[100:101], v80 offset:0x3400
	ds_read_b64_tr_b16 v[102:103], v80 offset:0x3c00
	s_waitcnt lgkmcnt(0)
	v_mfma_f32_32x32x16_bf16 v[18:33], v[68:71], v[88:91], v[18:33]
	ds_read_b64_tr_b16 v[88:89], v80 offset:0x600
	ds_read_b64_tr_b16 v[90:91], v80 offset:0xe00
	v_mfma_f32_32x32x16_bf16 v[18:33], v[72:75], v[92:95], v[18:33]
	ds_read_b64_tr_b16 v[92:93], v80 offset:0x1600
	ds_read_b64_tr_b16 v[94:95], v80 offset:0x1e00
	v_mfma_f32_32x32x16_bf16 v[18:33], v[76:79], v[96:99], v[18:33]
	ds_read_b64_tr_b16 v[96:97], v80 offset:0x2600
	ds_read_b64_tr_b16 v[98:99], v80 offset:0x2e00
	v_mfma_f32_32x32x16_bf16 v[18:33], v[84:87], v[100:103], v[18:33]
	ds_read_b64_tr_b16 v[100:101], v80 offset:0x3600
	ds_read_b64_tr_b16 v[102:103], v80 offset:0x3e00
	s_waitcnt lgkmcnt(0)
	v_mfma_f32_32x32x16_bf16 v[2:17], v[68:71], v[88:91], v[2:17]
	v_mfma_f32_32x32x16_bf16 v[2:17], v[72:75], v[92:95], v[2:17]
	v_mfma_f32_32x32x16_bf16 v[2:17], v[76:79], v[96:99], v[2:17]
	v_mfma_f32_32x32x16_bf16 v[2:17], v[84:87], v[100:103], v[2:17]
	s_and_saveexec_b64 s[2:3], s[6:7]
	v_add_f32_e32 v0, v0, v82
	v_fmac_f32_e32 v0, v195, v176
	v_add_f32_e32 v66, v66, v67
	v_fmac_f32_e32 v66, v0, v83
	ds_write_b32 v167, v66
	s_or_b64 exec, exec, s[2:3]
	s_waitcnt lgkmcnt(0)
	v_add_u32_e32 v0, s9, v166
	ds_read_b128 v[66:69], v0
	ds_read_b128 v[70:73], v0 offset:32
	ds_read_b128 v[74:77], v0 offset:64
	ds_read_b128 v[78:81], v0 offset:96
	s_mul_hi_i32 s3, s14, 0x1800
	s_mulk_i32 s14, 0x1800
	s_add_u32 s2, s4, s14
	s_addc_u32 s3, s5, s3
	v_and_b32_e32 v83, 0x1c0, v184
	v_lshlrev_b32_e32 v83, 7, v83
	v_and_b32_e32 v82, 32, v184
	v_lshl_or_b32 v83, v82, 5, v83
	v_and_b32_e32 v82, 31, v184
	v_lshl_or_b32 v83, v82, 1, v83
	s_waitcnt lgkmcnt(0)
	s_barrier
; __device__ __forceinline__ unsigned cvt_pk_bf16(float lo, float hi) { unsigned r; asm volatile("v_cvt_pk_bf16_f32 %0, %1, %2" : "=v"(r) : "v"(lo), "v"(hi)); return r; }
; __device__ __forceinline__ int crow(int r, int hi) { return (r & 3) + 8 * (r >> 2) + 4 * hi; }
; template <bool MLA> ...
;     ...
;   if (hi == 0) li_l[r32] = l_reg; asm volatile("s_waitcnt lgkmcnt(0)" ::: "memory");
;   float rli[16];
; #pragma unroll
;   for (int r = 0; r < 16; ++r) rli[r] = __builtin_amdgcn_rcpf(li_l[crow(r, hi)]);
;   bf16_t* Ow = Ob + (long)(wid * QBLK) * LDO;
; #pragma unroll
;   for (int r = 0; r < 16; ++r) { int orow = crow(r, hi);
; #pragma unroll
;     for (int d0 = 0; d0 < 4; ++d0) Ow[(long)orow * LDO + d0 * 32 + r32] = (bf16_t)(cvt_pk_bf16(o[d0][r] * rli[r], 0.f) & 0xffffu); }
	v_rcp_f32_e32 v66, v66
	v_rcp_f32_e32 v67, v67
	v_rcp_f32_e32 v68, v68
	v_rcp_f32_e32 v69, v69
	v_rcp_f32_e32 v70, v70
	v_rcp_f32_e32 v71, v71
	v_rcp_f32_e32 v72, v72
	v_rcp_f32_e32 v73, v73
	v_rcp_f32_e32 v74, v74
	v_rcp_f32_e32 v75, v75
	v_rcp_f32_e32 v76, v76
	v_rcp_f32_e32 v77, v77
	v_rcp_f32_e32 v78, v78
	v_rcp_f32_e32 v79, v79
	v_rcp_f32_e32 v80, v80
	v_rcp_f32_e32 v81, v81
	s_nop 0
	v_mul_f32_e32 v82, v50, v66
	v_cvt_pk_bf16_f32 v82, v82, v1
	ds_write_b16 v83, v82 offset:0
	v_mul_f32_e32 v0, v34, v66
	v_cvt_pk_bf16_f32 v0, v0, v1
	ds_write_b16 v83, v0 offset:64
	v_mul_f32_e32 v82, v18, v66
	v_cvt_pk_bf16_f32 v82, v82, v1
	ds_write_b16 v83, v82 offset:128
	v_mul_f32_e32 v0, v2, v66
	v_cvt_pk_bf16_f32 v0, v0, v1
	ds_write_b16 v83, v0 offset:192
	v_mul_f32_e32 v82, v51, v67
	v_cvt_pk_bf16_f32 v82, v82, v1
	ds_write_b16 v83, v82 offset:256
	v_mul_f32_e32 v0, v35, v67
	v_cvt_pk_bf16_f32 v0, v0, v1
	ds_write_b16 v83, v0 offset:320
	v_mul_f32_e32 v82, v19, v67
	v_cvt_pk_bf16_f32 v82, v82, v1
	ds_write_b16 v83, v82 offset:384
	v_mul_f32_e32 v0, v3, v67
	v_cvt_pk_bf16_f32 v0, v0, v1
	ds_write_b16 v83, v0 offset:448
	v_mul_f32_e32 v82, v52, v68
	v_cvt_pk_bf16_f32 v82, v82, v1
	ds_write_b16 v83, v82 offset:512
	v_mul_f32_e32 v0, v36, v68
	v_cvt_pk_bf16_f32 v0, v0, v1
	ds_write_b16 v83, v0 offset:576
	v_mul_f32_e32 v82, v20, v68
	v_cvt_pk_bf16_f32 v82, v82, v1
	ds_write_b16 v83, v82 offset:640
	v_mul_f32_e32 v0, v4, v68
	v_cvt_pk_bf16_f32 v0, v0, v1
	ds_write_b16 v83, v0 offset:704
	v_mul_f32_e32 v82, v53, v69
	v_cvt_pk_bf16_f32 v82, v82, v1
	ds_write_b16 v83, v82 offset:768
	v_mul_f32_e32 v0, v37, v69
	v_cvt_pk_bf16_f32 v0, v0, v1
	ds_write_b16 v83, v0 offset:832
	v_mul_f32_e32 v82, v21, v69
	v_cvt_pk_bf16_f32 v82, v82, v1
	ds_write_b16 v83, v82 offset:896
	v_mul_f32_e32 v0, v5, v69
	v_cvt_pk_bf16_f32 v0, v0, v1
	ds_write_b16 v83, v0 offset:960
	v_mul_f32_e32 v82, v54, v70
	v_cvt_pk_bf16_f32 v82, v82, v1
	ds_write_b16 v83, v82 offset:2048
	v_mul_f32_e32 v0, v38, v70
	v_cvt_pk_bf16_f32 v0, v0, v1
	ds_write_b16 v83, v0 offset:2112
	v_mul_f32_e32 v82, v22, v70
	v_cvt_pk_bf16_f32 v82, v82, v1
	ds_write_b16 v83, v82 offset:2176
	v_mul_f32_e32 v0, v6, v70
	v_cvt_pk_bf16_f32 v0, v0, v1
	ds_write_b16 v83, v0 offset:2240
	v_mul_f32_e32 v82, v55, v71
	v_cvt_pk_bf16_f32 v82, v82, v1
	ds_write_b16 v83, v82 offset:2304
	v_mul_f32_e32 v0, v39, v71
	v_cvt_pk_bf16_f32 v0, v0, v1
	ds_write_b16 v83, v0 offset:2368
	v_mul_f32_e32 v82, v23, v71
	v_cvt_pk_bf16_f32 v82, v82, v1
	ds_write_b16 v83, v82 offset:2432
	v_mul_f32_e32 v0, v7, v71
	v_cvt_pk_bf16_f32 v0, v0, v1
	ds_write_b16 v83, v0 offset:2496
	v_mul_f32_e32 v82, v56, v72
	v_cvt_pk_bf16_f32 v82, v82, v1
	ds_write_b16 v83, v82 offset:2560
	v_mul_f32_e32 v0, v40, v72
	v_cvt_pk_bf16_f32 v0, v0, v1
	ds_write_b16 v83, v0 offset:2624
	v_mul_f32_e32 v82, v24, v72
	v_cvt_pk_bf16_f32 v82, v82, v1
	ds_write_b16 v83, v82 offset:2688
	v_mul_f32_e32 v0, v8, v72
	v_cvt_pk_bf16_f32 v0, v0, v1
	ds_write_b16 v83, v0 offset:2752
	v_mul_f32_e32 v82, v57, v73
	v_cvt_pk_bf16_f32 v82, v82, v1
	ds_write_b16 v83, v82 offset:2816
	v_mul_f32_e32 v0, v41, v73
	v_cvt_pk_bf16_f32 v0, v0, v1
	ds_write_b16 v83, v0 offset:2880
	v_mul_f32_e32 v82, v25, v73
	v_cvt_pk_bf16_f32 v82, v82, v1
	ds_write_b16 v83, v82 offset:2944
	v_mul_f32_e32 v0, v9, v73
	v_cvt_pk_bf16_f32 v0, v0, v1
	ds_write_b16 v83, v0 offset:3008
	v_mul_f32_e32 v82, v58, v74
	v_cvt_pk_bf16_f32 v82, v82, v1
	ds_write_b16 v83, v82 offset:4096
	v_mul_f32_e32 v0, v42, v74
	v_cvt_pk_bf16_f32 v0, v0, v1
	ds_write_b16 v83, v0 offset:4160
	v_mul_f32_e32 v82, v26, v74
	v_cvt_pk_bf16_f32 v82, v82, v1
	ds_write_b16 v83, v82 offset:4224
	v_mul_f32_e32 v0, v10, v74
	v_cvt_pk_bf16_f32 v0, v0, v1
	ds_write_b16 v83, v0 offset:4288
	v_mul_f32_e32 v82, v59, v75
	v_cvt_pk_bf16_f32 v82, v82, v1
	ds_write_b16 v83, v82 offset:4352
	v_mul_f32_e32 v0, v43, v75
	v_cvt_pk_bf16_f32 v0, v0, v1
	ds_write_b16 v83, v0 offset:4416
	v_mul_f32_e32 v82, v27, v75
	v_cvt_pk_bf16_f32 v82, v82, v1
	ds_write_b16 v83, v82 offset:4480
	v_mul_f32_e32 v0, v11, v75
	v_cvt_pk_bf16_f32 v0, v0, v1
	ds_write_b16 v83, v0 offset:4544
	v_mul_f32_e32 v82, v60, v76
	v_cvt_pk_bf16_f32 v82, v82, v1
	ds_write_b16 v83, v82 offset:4608
	v_mul_f32_e32 v0, v44, v76
	v_cvt_pk_bf16_f32 v0, v0, v1
	ds_write_b16 v83, v0 offset:4672
	v_mul_f32_e32 v82, v28, v76
	v_cvt_pk_bf16_f32 v82, v82, v1
	ds_write_b16 v83, v82 offset:4736
	v_mul_f32_e32 v0, v12, v76
	v_cvt_pk_bf16_f32 v0, v0, v1
	ds_write_b16 v83, v0 offset:4800
	v_mul_f32_e32 v82, v61, v77
	v_cvt_pk_bf16_f32 v82, v82, v1
	ds_write_b16 v83, v82 offset:4864
	v_mul_f32_e32 v0, v45, v77
	v_cvt_pk_bf16_f32 v0, v0, v1
	ds_write_b16 v83, v0 offset:4928
	v_mul_f32_e32 v82, v29, v77
	v_cvt_pk_bf16_f32 v82, v82, v1
	ds_write_b16 v83, v82 offset:4992
	v_mul_f32_e32 v0, v13, v77
	v_cvt_pk_bf16_f32 v0, v0, v1
	ds_write_b16 v83, v0 offset:5056
	v_mul_f32_e32 v82, v62, v78
	v_cvt_pk_bf16_f32 v82, v82, v1
	ds_write_b16 v83, v82 offset:6144
	v_mul_f32_e32 v0, v46, v78
	v_cvt_pk_bf16_f32 v0, v0, v1
	ds_write_b16 v83, v0 offset:6208
	v_mul_f32_e32 v82, v30, v78
	v_cvt_pk_bf16_f32 v82, v82, v1
	ds_write_b16 v83, v82 offset:6272
	v_mul_f32_e32 v0, v14, v78
	v_cvt_pk_bf16_f32 v0, v0, v1
	ds_write_b16 v83, v0 offset:6336
	v_mul_f32_e32 v82, v63, v79
	v_cvt_pk_bf16_f32 v82, v82, v1
	ds_write_b16 v83, v82 offset:6400
	v_mul_f32_e32 v0, v47, v79
	v_cvt_pk_bf16_f32 v0, v0, v1
	ds_write_b16 v83, v0 offset:6464
	v_mul_f32_e32 v82, v31, v79
	v_cvt_pk_bf16_f32 v82, v82, v1
	ds_write_b16 v83, v82 offset:6528
	v_mul_f32_e32 v0, v15, v79
	v_cvt_pk_bf16_f32 v0, v0, v1
	ds_write_b16 v83, v0 offset:6592
	v_mul_f32_e32 v82, v64, v80
	v_cvt_pk_bf16_f32 v82, v82, v1
	ds_write_b16 v83, v82 offset:6656
	v_mul_f32_e32 v0, v48, v80
	v_cvt_pk_bf16_f32 v0, v0, v1
	ds_write_b16 v83, v0 offset:6720
	v_mul_f32_e32 v82, v32, v80
	v_cvt_pk_bf16_f32 v82, v82, v1
	ds_write_b16 v83, v82 offset:6784
	v_mul_f32_e32 v0, v16, v80
	v_cvt_pk_bf16_f32 v0, v0, v1
	ds_write_b16 v83, v0 offset:6848
	v_mul_f32_e32 v82, v65, v81
	v_cvt_pk_bf16_f32 v82, v82, v1
	ds_write_b16 v83, v82 offset:6912
	v_mul_f32_e32 v0, v49, v81
	v_cvt_pk_bf16_f32 v0, v0, v1
	ds_write_b16 v83, v0 offset:6976
	v_mul_f32_e32 v82, v33, v81
	v_cvt_pk_bf16_f32 v82, v82, v1
	ds_write_b16 v83, v82 offset:7040
	v_mul_f32_e32 v0, v17, v81
	v_cvt_pk_bf16_f32 v0, v0, v1
	ds_write_b16 v83, v0 offset:7104
	s_waitcnt lgkmcnt(0)
; __device__ __forceinline__ unsigned cvt_pk_bf16(float lo, float hi) { unsigned r; asm volatile("v_cvt_pk_bf16_f32 %0, %1, %2" : "=v"(r) : "v"(lo), "v"(hi)); return r; }
; __device__ __forceinline__ int crow(int r, int hi) { return (r & 3) + 8 * (r >> 2) + 4 * hi; }
; template <bool MLA> ...
;     ...
;   bf16_t* Ow = Ob + (long)(wid * QBLK) * LDO;
; #pragma unroll
;   for (int r = 0; r < 16; ++r) { int orow = crow(r, hi);
; #pragma unroll
;     for (int d0 = 0; d0 < 4; ++d0) Ow[(long)orow * LDO + d0 * 32 + r32] = (bf16_t)(cvt_pk_bf16(o[d0][r] * rli[r], 0.f) & 0xffffu); }
;   __syncthreads();
	v_and_b32_e32 v2, 0x1c0, v184
	v_lshlrev_b32_e32 v2, 7, v2
	v_and_b32_e32 v3, 63, v184
	v_lshl_or_b32 v2, v3, 4, v2
	ds_read_b128 v[4:7], v2 offset:0
	ds_read_b128 v[8:11], v2 offset:1024
	ds_read_b128 v[12:15], v2 offset:2048
	ds_read_b128 v[16:19], v2 offset:3072
	ds_read_b128 v[20:23], v2 offset:4096
	ds_read_b128 v[24:27], v2 offset:5120
	ds_read_b128 v[28:31], v2 offset:6144
	ds_read_b128 v[32:35], v2 offset:7168
	v_bfe_u32 v36, v184, 4, 2
	v_mul_u32_u24_e32 v36, 0x1800, v36
	v_and_b32_e32 v37, 15, v184
	v_lshl_or_b32 v36, v37, 4, v36
	v_mov_b32_e32 v37, 0
	v_lshl_add_u64 v[38:39], s[2:3], 0, v[36:37]
	s_mov_b64 vcc, 0x6000
	v_lshl_add_u64 v[40:41], v[38:39], 0, vcc
	v_lshl_add_u64 v[42:43], v[40:41], 0, vcc
	v_lshl_add_u64 v[44:45], v[42:43], 0, vcc
	v_lshl_add_u64 v[46:47], v[44:45], 0, vcc
	v_lshl_add_u64 v[48:49], v[46:47], 0, vcc
	v_lshl_add_u64 v[50:51], v[48:49], 0, vcc
	v_lshl_add_u64 v[52:53], v[50:51], 0, vcc
	s_waitcnt lgkmcnt(7)
	global_store_dwordx4 v[38:39], v[4:7], off offset:2048
	s_waitcnt lgkmcnt(6)
	global_store_dwordx4 v[40:41], v[8:11], off offset:2048
	s_waitcnt lgkmcnt(5)
	global_store_dwordx4 v[42:43], v[12:15], off offset:2048
	s_waitcnt lgkmcnt(4)
	global_store_dwordx4 v[44:45], v[16:19], off offset:2048
	s_waitcnt lgkmcnt(3)
	global_store_dwordx4 v[46:47], v[20:23], off offset:2048
	s_waitcnt lgkmcnt(2)
	global_store_dwordx4 v[48:49], v[24:27], off offset:2048
	s_waitcnt lgkmcnt(1)
	global_store_dwordx4 v[50:51], v[28:31], off offset:2048
	s_waitcnt lgkmcnt(0)
	global_store_dwordx4 v[52:53], v[32:35], off offset:2048
	s_waitcnt vmcnt(63) expcnt(7) lgkmcnt(15)
	s_barrier
	s_branch .LBB0_98
